# neighbourhood-attention key loop hand-rewritten on top of the pipelined MLA loop: straight-line masks via v_cndmask, unconditional bias reads, global loads one step ahead
# baseline (speedup 1.0000x reference)
; #define MFMA(a, b, c) __builtin_amdgcn_mfma_f32_32x32x16_bf16((a), (b), (c), 0, 0, 0)
;   DI u16* nak() const { return (u16*)(ws + O_NAK); }
; DI void na_item(const Ctx& c, const float* __restrict__ bias, int b, int row, int head, int qt) {
;     ...
; #pragma unroll 1
;   for (int kri = 0; kri < 8; ++kri) {
;     const int krow = rstart + kri;
;     const float* bl = bias + (head * 15 + (krow - row + 7)) * 31;
; #pragma unroll
;     for (int kk = 0; kk < 2; ++kk) {
;       const u16* kp = c.nak() + (size_t)(s0 + krow * 64 + kk * 32 + pr) * 256 + head * 64 + hh * 8;
;       bf16x8 kf[4];
; #pragma unroll
;       for (int ks = 0; ks < 4; ++ks) kf[ks] = ldg8(kp + ks * 16);
;       bf16x8 vf[2][2];
; #pragma unroll
;       for (int dt = 0; dt < 2; ++dt)
; #pragma unroll
;         for (int s2 = 0; s2 < 2; ++s2) vf[dt][s2] = ldg8(VT + (size_t)(dt * 32 + r32) * Lb + krow * 64 + kk * 32 + s2 * 16 + hh * 8);
;       f32x16 s;
;       zero_acc(s);
; #pragma unroll
;       for (int ks = 0; ks < 4; ++ks) s = MFMA(kf[ks], qf[ks], s);
;       float ls = 0.f;
; #pragma unroll
;       for (int i = 0; i < 16; ++i) {
;         const int kc = kk * 32 + 16 * ((i >> 3) & 1) + 8 * hh + 4 * ((i >> 2) & 1) + (i & 3);
;         const bool valid = (kc >= cs) && (kc < cs + 16);
;         const int bi = min(max(kc - qc + 15, 0), 30);
;         const float p = valid ? __builtin_amdgcn_exp2f(s[i] + bl[bi]) : 0.f;
;         s[i] = p; ls += p;
;       }
;       lsum += ls;
;       const bf16x8 pf0 = pack8(s, 0), pf1 = pack8(s, 1);
; #pragma unroll
;       for (int dt = 0; dt < 2; ++dt) {
;         o[dt] = MFMA(vf[dt][0], pf0, o[dt]);
;         o[dt] = MFMA(vf[dt][1], pf1, o[dt]);
;       }
;     }
;   }
.LBB0_523:
	v_subrev_u32_e32 v32, 32, v96
	v_ashrrev_i32_e32 v33, 31, v32
	v_lshlrev_b64 v[32:33], 9, v[32:33]
	v_lshl_add_u64 v[186:187], v[90:91], 0, v[32:33]
	s_mov_b64 s[44:45], 0x4000
	global_load_dwordx4 v[190:193], v[186:187], off
	global_load_dwordx4 v[194:197], v[186:187], off offset:32
	global_load_dwordx4 v[198:201], v[186:187], off offset:64
	global_load_dwordx4 v[202:205], v[186:187], off offset:96
	global_load_dwordx4 v[206:209], v[92:93], off offset:-64
	global_load_dwordx4 v[210:213], v[92:93], off offset:-32
	global_load_dwordx4 v[214:217], v[94:95], off offset:-64
	global_load_dwordx4 v[218:221], v[94:95], off offset:-32
.Lna_loop:
	v_lshl_add_u64 v[188:189], v[186:187], 0, s[44:45]
	global_load_dwordx4 v[64:67], v[188:189], off
	global_load_dwordx4 v[68:71], v[188:189], off offset:32
	global_load_dwordx4 v[72:75], v[188:189], off offset:64
	global_load_dwordx4 v[76:79], v[188:189], off offset:96
	global_load_dwordx4 v[170:173], v[92:93], off
	global_load_dwordx4 v[174:177], v[92:93], off offset:32
	global_load_dwordx4 v[178:181], v[94:95], off
	global_load_dwordx4 v[182:185], v[94:95], off offset:32
	ds_read_b32 v222, v148
	ds_read_b32 v223, v147
	ds_read_b32 v224, v146
	ds_read_b32 v225, v145
	ds_read_b32 v226, v144
	ds_read_b32 v227, v143
	ds_read_b32 v228, v142
	ds_read_b32 v229, v141
	ds_read_b32 v230, v149
	ds_read_b32 v231, v150
	ds_read_b32 v232, v151
	ds_read_b32 v233, v152
	ds_read_b32 v234, v153
	ds_read_b32 v235, v154
	ds_read_b32 v236, v155
	ds_read_b32 v237, v156
	s_waitcnt vmcnt(8)
	v_mfma_f32_32x32x16_bf16 v[32:47], v[190:193], v[48:51], 0
	v_mfma_f32_32x32x16_bf16 v[32:47], v[194:197], v[52:55], v[32:47]
	v_mfma_f32_32x32x16_bf16 v[32:47], v[198:201], v[56:59], v[32:47]
	v_mfma_f32_32x32x16_bf16 v[32:47], v[202:205], v[60:63], v[32:47]
	v_add_u32_e32 v148, 0x7c, v148
	v_add_u32_e32 v147, 0x7c, v147
	v_add_u32_e32 v146, 0x7c, v146
	v_add_u32_e32 v145, 0x7c, v145
	v_add_u32_e32 v144, 0x7c, v144
	v_add_u32_e32 v143, 0x7c, v143
	v_add_u32_e32 v142, 0x7c, v142
	v_add_u32_e32 v141, 0x7c, v141
	v_add_u32_e32 v149, 0x7c, v149
	v_add_u32_e32 v150, 0x7c, v150
	v_add_u32_e32 v151, 0x7c, v151
	v_add_u32_e32 v152, 0x7c, v152
	v_add_u32_e32 v153, 0x7c, v153
	v_add_u32_e32 v154, 0x7c, v154
	v_add_u32_e32 v155, 0x7c, v155
	v_add_u32_e32 v156, 0x7c, v156
	s_waitcnt lgkmcnt(0)
	v_add_f32_e32 v32, v32, v222
	v_add_f32_e32 v33, v33, v223
	v_add_f32_e32 v34, v34, v224
	v_add_f32_e32 v35, v35, v225
	v_add_f32_e32 v36, v36, v226
	v_add_f32_e32 v37, v37, v227
	v_add_f32_e32 v38, v38, v228
	v_add_f32_e32 v39, v39, v229
	v_add_f32_e32 v40, v40, v230
	v_add_f32_e32 v41, v41, v231
	v_add_f32_e32 v42, v42, v232
	v_add_f32_e32 v43, v43, v233
	v_add_f32_e32 v44, v44, v234
	v_add_f32_e32 v45, v45, v235
	v_add_f32_e32 v46, v46, v236
	v_add_f32_e32 v47, v47, v237
	v_exp_f32_e32 v32, v32
	v_exp_f32_e32 v33, v33
	v_exp_f32_e32 v34, v34
	v_exp_f32_e32 v35, v35
	v_exp_f32_e32 v36, v36
	v_exp_f32_e32 v37, v37
	v_exp_f32_e32 v38, v38
	v_exp_f32_e32 v39, v39
	v_exp_f32_e32 v40, v40
	v_exp_f32_e32 v41, v41
	v_exp_f32_e32 v42, v42
	v_exp_f32_e32 v43, v43
	v_exp_f32_e32 v44, v44
	v_exp_f32_e32 v45, v45
	v_exp_f32_e32 v46, v46
	v_exp_f32_e32 v47, v47
	v_cndmask_b32_e32 v32, 0, v32, vcc
	v_cndmask_b32_e64 v33, 0, v33, s[0:1]
	v_cndmask_b32_e64 v34, 0, v34, s[30:31]
	v_cndmask_b32_e64 v35, 0, v35, s[4:5]
	v_cndmask_b32_e64 v36, 0, v36, s[6:7]
	v_cndmask_b32_e64 v37, 0, v37, s[8:9]
	v_cndmask_b32_e64 v38, 0, v38, s[10:11]
	v_cndmask_b32_e64 v39, 0, v39, s[12:13]
	v_cndmask_b32_e64 v40, 0, v40, s[96:97]
	v_cndmask_b32_e64 v41, 0, v41, s[92:93]
	v_cndmask_b32_e64 v42, 0, v42, s[56:57]
	v_cndmask_b32_e64 v43, 0, v43, s[84:85]
	v_cndmask_b32_e64 v44, 0, v44, s[86:87]
	v_cndmask_b32_e64 v45, 0, v45, s[88:89]
	v_cndmask_b32_e64 v46, 0, v46, s[90:91]
	v_cndmask_b32_e64 v47, 0, v47, s[66:67]
	v_cvt_pk_bf16_f32 v242, v32, v33
	v_cvt_pk_bf16_f32 v243, v34, v35
	v_cvt_pk_bf16_f32 v244, v36, v37
	v_cvt_pk_bf16_f32 v245, v38, v39
	v_cvt_pk_bf16_f32 v246, v40, v41
	v_cvt_pk_bf16_f32 v247, v42, v43
	v_cvt_pk_bf16_f32 v248, v44, v45
	v_cvt_pk_bf16_f32 v249, v46, v47
	v_add_f32_e32 v97, v32, v33
	v_add_f32_e32 v169, v34, v35
	v_add_f32_e32 v97, v97, v36
	v_add_f32_e32 v169, v169, v37
	v_add_f32_e32 v97, v97, v38
	v_add_f32_e32 v169, v169, v39
	v_add_f32_e32 v97, v97, v40
	v_add_f32_e32 v169, v169, v41
	v_add_f32_e32 v97, v97, v42
	v_add_f32_e32 v169, v169, v43
	v_add_f32_e32 v97, v97, v44
	v_add_f32_e32 v169, v169, v45
	v_add_f32_e32 v97, v97, v46
	v_add_f32_e32 v169, v169, v47
	v_mfma_f32_32x32x16_bf16 v[16:31], v[206:209], v[242:245], v[16:31]
	v_mfma_f32_32x32x16_bf16 v[0:15], v[214:217], v[242:245], v[0:15]
	v_add_f32_e32 v97, v97, v169
	v_mfma_f32_32x32x16_bf16 v[16:31], v[210:213], v[246:249], v[16:31]
	v_mfma_f32_32x32x16_bf16 v[0:15], v[218:221], v[246:249], v[0:15]
	v_add_f32_e32 v166, v166, v97
	s_mov_b64 s[34:35], 0x8000
	v_lshl_add_u64 v[186:187], v[186:187], 0, s[34:35]
	s_mov_b64 s[34:35], 0x80
	v_lshl_add_u64 v[92:93], v[92:93], 0, s[34:35]
	v_lshl_add_u64 v[94:95], v[94:95], 0, s[34:35]
	ds_read_b32 v222, v157
	ds_read_b32 v223, v158
	ds_read_b32 v224, v159
	ds_read_b32 v225, v160
	ds_read_b32 v226, v161
	ds_read_b32 v227, v162
	ds_read_b32 v228, v163
	ds_read_b32 v229, v164
	ds_read_b32 v230, v167
	ds_read_b32 v231, v168
	ds_read_b32 v232, v140
	ds_read_b32 v233, v139
	ds_read_b32 v234, v138
	ds_read_b32 v235, v137
	ds_read_b32 v236, v136
	ds_read_b32 v237, v135
	s_cmpk_eq_i32 s36, 7
	s_cbranch_scc1 .Lna_last
; #define MFMA(a, b, c) __builtin_amdgcn_mfma_f32_32x32x16_bf16((a), (b), (c), 0, 0, 0)
;   DI u16* nak() const { return (u16*)(ws + O_NAK); }
; DI void na_item(const Ctx& c, const float* __restrict__ bias, int b, int row, int head, int qt) {
;     ...
;     for (int kk = 0; kk < 2; ++kk) {
;       const u16* kp = c.nak() + (size_t)(s0 + krow * 64 + kk * 32 + pr) * 256 + head * 64 + hh * 8;
;       bf16x8 kf[4];
; #pragma unroll
;       for (int ks = 0; ks < 4; ++ks) kf[ks] = ldg8(kp + ks * 16);
;       bf16x8 vf[2][2];
; #pragma unroll
;       for (int dt = 0; dt < 2; ++dt)
; #pragma unroll
;         for (int s2 = 0; s2 < 2; ++s2) vf[dt][s2] = ldg8(VT + (size_t)(dt * 32 + r32) * Lb + krow * 64 + kk * 32 + s2 * 16 + hh * 8);
;       f32x16 s;
;       zero_acc(s);
; #pragma unroll
;       for (int ks = 0; ks < 4; ++ks) s = MFMA(kf[ks], qf[ks], s);
;       float ls = 0.f;
; #pragma unroll
;       for (int i = 0; i < 16; ++i) {
;         const int kc = kk * 32 + 16 * ((i >> 3) & 1) + 8 * hh + 4 * ((i >> 2) & 1) + (i & 3);
;         const bool valid = (kc >= cs) && (kc < cs + 16);
;         const int bi = min(max(kc - qc + 15, 0), 30);
;         const float p = valid ? __builtin_amdgcn_exp2f(s[i] + bl[bi]) : 0.f;
;         s[i] = p; ls += p;
;       }
;       lsum += ls;
;       const bf16x8 pf0 = pack8(s, 0), pf1 = pack8(s, 1);
; #pragma unroll
;       for (int dt = 0; dt < 2; ++dt) {
;         o[dt] = MFMA(vf[dt][0], pf0, o[dt]);
;         o[dt] = MFMA(vf[dt][1], pf1, o[dt]);
;       }
;     }
	global_load_dwordx4 v[190:193], v[186:187], off
	global_load_dwordx4 v[194:197], v[186:187], off offset:32
	global_load_dwordx4 v[198:201], v[186:187], off offset:64
	global_load_dwordx4 v[202:205], v[186:187], off offset:96
	global_load_dwordx4 v[206:209], v[92:93], off offset:-64
	global_load_dwordx4 v[210:213], v[92:93], off offset:-32
	global_load_dwordx4 v[214:217], v[94:95], off offset:-64
	global_load_dwordx4 v[218:221], v[94:95], off offset:-32
	s_waitcnt vmcnt(8)
	v_mfma_f32_32x32x16_bf16 v[32:47], v[64:67], v[48:51], 0
	v_mfma_f32_32x32x16_bf16 v[32:47], v[68:71], v[52:55], v[32:47]
	v_mfma_f32_32x32x16_bf16 v[32:47], v[72:75], v[56:59], v[32:47]
	v_mfma_f32_32x32x16_bf16 v[32:47], v[76:79], v[60:63], v[32:47]
	v_add_u32_e32 v157, 0x7c, v157
	v_add_u32_e32 v158, 0x7c, v158
	v_add_u32_e32 v159, 0x7c, v159
	v_add_u32_e32 v160, 0x7c, v160
	v_add_u32_e32 v161, 0x7c, v161
	v_add_u32_e32 v162, 0x7c, v162
	v_add_u32_e32 v163, 0x7c, v163
	v_add_u32_e32 v164, 0x7c, v164
	v_add_u32_e32 v167, 0x7c, v167
	v_add_u32_e32 v168, 0x7c, v168
	v_add_u32_e32 v140, 0x7c, v140
	v_add_u32_e32 v139, 0x7c, v139
	v_add_u32_e32 v138, 0x7c, v138
	v_add_u32_e32 v137, 0x7c, v137
	v_add_u32_e32 v136, 0x7c, v136
	v_add_u32_e32 v135, 0x7c, v135
	s_waitcnt lgkmcnt(0)
	v_add_f32_e32 v32, v32, v222
	v_add_f32_e32 v33, v33, v223
	v_add_f32_e32 v34, v34, v224
	v_add_f32_e32 v35, v35, v225
	v_add_f32_e32 v36, v36, v226
	v_add_f32_e32 v37, v37, v227
	v_add_f32_e32 v38, v38, v228
	v_add_f32_e32 v39, v39, v229
	v_add_f32_e32 v40, v40, v230
	v_add_f32_e32 v41, v41, v231
	v_add_f32_e32 v42, v42, v232
	v_add_f32_e32 v43, v43, v233
	v_add_f32_e32 v44, v44, v234
	v_add_f32_e32 v45, v45, v235
	v_add_f32_e32 v46, v46, v236
	v_add_f32_e32 v47, v47, v237
	v_exp_f32_e32 v32, v32
	v_exp_f32_e32 v33, v33
	v_exp_f32_e32 v34, v34
	v_exp_f32_e32 v35, v35
	v_exp_f32_e32 v36, v36
	v_exp_f32_e32 v37, v37
	v_exp_f32_e32 v38, v38
	v_exp_f32_e32 v39, v39
	v_exp_f32_e32 v40, v40
	v_exp_f32_e32 v41, v41
	v_exp_f32_e32 v42, v42
	v_exp_f32_e32 v43, v43
	v_exp_f32_e32 v44, v44
	v_exp_f32_e32 v45, v45
	v_exp_f32_e32 v46, v46
	v_exp_f32_e32 v47, v47
	v_cndmask_b32_e64 v32, 0, v32, s[54:55]
	v_cndmask_b32_e64 v33, 0, v33, s[60:61]
	v_cndmask_b32_e64 v34, 0, v34, s[64:65]
	v_cndmask_b32_e64 v35, 0, v35, s[62:63]
	v_cndmask_b32_e64 v36, 0, v36, s[94:95]
	v_cndmask_b32_e64 v37, 0, v37, s[52:53]
	v_cndmask_b32_e64 v38, 0, v38, s[2:3]
	v_cndmask_b32_e64 v39, 0, v39, s[58:59]
	v_cndmask_b32_e64 v40, 0, v40, s[14:15]
	v_cndmask_b32_e64 v41, 0, v41, s[16:17]
	v_cndmask_b32_e64 v42, 0, v42, s[18:19]
	v_cndmask_b32_e64 v43, 0, v43, s[20:21]
	v_cndmask_b32_e64 v44, 0, v44, s[22:23]
	v_cndmask_b32_e64 v45, 0, v45, s[24:25]
	v_cndmask_b32_e64 v46, 0, v46, s[26:27]
	v_cndmask_b32_e64 v47, 0, v47, s[28:29]
	v_cvt_pk_bf16_f32 v242, v32, v33
	v_cvt_pk_bf16_f32 v243, v34, v35
	v_cvt_pk_bf16_f32 v244, v36, v37
	v_cvt_pk_bf16_f32 v245, v38, v39
	v_cvt_pk_bf16_f32 v246, v40, v41
	v_cvt_pk_bf16_f32 v247, v42, v43
	v_cvt_pk_bf16_f32 v248, v44, v45
	v_cvt_pk_bf16_f32 v249, v46, v47
	v_add_f32_e32 v97, v32, v33
	v_add_f32_e32 v169, v34, v35
	v_add_f32_e32 v97, v97, v36
	v_add_f32_e32 v169, v169, v37
	v_add_f32_e32 v97, v97, v38
	v_add_f32_e32 v169, v169, v39
	v_add_f32_e32 v97, v97, v40
	v_add_f32_e32 v169, v169, v41
	v_add_f32_e32 v97, v97, v42
	v_add_f32_e32 v169, v169, v43
	v_add_f32_e32 v97, v97, v44
	v_add_f32_e32 v169, v169, v45
	v_add_f32_e32 v97, v97, v46
	v_add_f32_e32 v169, v169, v47
	v_mfma_f32_32x32x16_bf16 v[16:31], v[170:173], v[242:245], v[16:31]
	v_mfma_f32_32x32x16_bf16 v[0:15], v[178:181], v[242:245], v[0:15]
	v_add_f32_e32 v97, v97, v169
	v_mfma_f32_32x32x16_bf16 v[16:31], v[174:177], v[246:249], v[16:31]
	v_mfma_f32_32x32x16_bf16 v[0:15], v[182:185], v[246:249], v[0:15]
	v_add_f32_e32 v166, v166, v97
	s_addk_i32 s36, 1
	s_branch .Lna_loop
; #define MFMA(a, b, c) __builtin_amdgcn_mfma_f32_32x32x16_bf16((a), (b), (c), 0, 0, 0)
;   DI u16* nak() const { return (u16*)(ws + O_NAK); }
; DI void na_item(const Ctx& c, const float* __restrict__ bias, int b, int row, int head, int qt) {
;     ...
;     for (int kk = 0; kk < 2; ++kk) {
;       const u16* kp = c.nak() + (size_t)(s0 + krow * 64 + kk * 32 + pr) * 256 + head * 64 + hh * 8;
;       bf16x8 kf[4];
; #pragma unroll
;       for (int ks = 0; ks < 4; ++ks) kf[ks] = ldg8(kp + ks * 16);
;       bf16x8 vf[2][2];
; #pragma unroll
;       for (int dt = 0; dt < 2; ++dt)
; #pragma unroll
;         for (int s2 = 0; s2 < 2; ++s2) vf[dt][s2] = ldg8(VT + (size_t)(dt * 32 + r32) * Lb + krow * 64 + kk * 32 + s2 * 16 + hh * 8);
;       f32x16 s;
;       zero_acc(s);
; #pragma unroll
;       for (int ks = 0; ks < 4; ++ks) s = MFMA(kf[ks], qf[ks], s);
;       float ls = 0.f;
; #pragma unroll
;       for (int i = 0; i < 16; ++i) {
;         const int kc = kk * 32 + 16 * ((i >> 3) & 1) + 8 * hh + 4 * ((i >> 2) & 1) + (i & 3);
;         const bool valid = (kc >= cs) && (kc < cs + 16);
;         const int bi = min(max(kc - qc + 15, 0), 30);
;         const float p = valid ? __builtin_amdgcn_exp2f(s[i] + bl[bi]) : 0.f;
;         s[i] = p; ls += p;
;       }
;       lsum += ls;
;       const bf16x8 pf0 = pack8(s, 0), pf1 = pack8(s, 1);
; #pragma unroll
;       for (int dt = 0; dt < 2; ++dt) {
;         o[dt] = MFMA(vf[dt][0], pf0, o[dt]);
;         o[dt] = MFMA(vf[dt][1], pf1, o[dt]);
;       }
;     }
.Lna_last:
	s_waitcnt vmcnt(0)
	v_mfma_f32_32x32x16_bf16 v[32:47], v[64:67], v[48:51], 0
	v_mfma_f32_32x32x16_bf16 v[32:47], v[68:71], v[52:55], v[32:47]
	v_mfma_f32_32x32x16_bf16 v[32:47], v[72:75], v[56:59], v[32:47]
	v_mfma_f32_32x32x16_bf16 v[32:47], v[76:79], v[60:63], v[32:47]
	v_add_u32_e32 v157, 0x7c, v157
	v_add_u32_e32 v158, 0x7c, v158
	v_add_u32_e32 v159, 0x7c, v159
	v_add_u32_e32 v160, 0x7c, v160
	v_add_u32_e32 v161, 0x7c, v161
	v_add_u32_e32 v162, 0x7c, v162
	v_add_u32_e32 v163, 0x7c, v163
	v_add_u32_e32 v164, 0x7c, v164
	v_add_u32_e32 v167, 0x7c, v167
	v_add_u32_e32 v168, 0x7c, v168
	v_add_u32_e32 v140, 0x7c, v140
	v_add_u32_e32 v139, 0x7c, v139
	v_add_u32_e32 v138, 0x7c, v138
	v_add_u32_e32 v137, 0x7c, v137
	v_add_u32_e32 v136, 0x7c, v136
	v_add_u32_e32 v135, 0x7c, v135
	s_waitcnt lgkmcnt(0)
	v_add_f32_e32 v32, v32, v222
	v_add_f32_e32 v33, v33, v223
	v_add_f32_e32 v34, v34, v224
	v_add_f32_e32 v35, v35, v225
	v_add_f32_e32 v36, v36, v226
	v_add_f32_e32 v37, v37, v227
	v_add_f32_e32 v38, v38, v228
	v_add_f32_e32 v39, v39, v229
	v_add_f32_e32 v40, v40, v230
	v_add_f32_e32 v41, v41, v231
	v_add_f32_e32 v42, v42, v232
	v_add_f32_e32 v43, v43, v233
	v_add_f32_e32 v44, v44, v234
	v_add_f32_e32 v45, v45, v235
	v_add_f32_e32 v46, v46, v236
	v_add_f32_e32 v47, v47, v237
	v_exp_f32_e32 v32, v32
	v_exp_f32_e32 v33, v33
	v_exp_f32_e32 v34, v34
	v_exp_f32_e32 v35, v35
	v_exp_f32_e32 v36, v36
	v_exp_f32_e32 v37, v37
	v_exp_f32_e32 v38, v38
	v_exp_f32_e32 v39, v39
	v_exp_f32_e32 v40, v40
	v_exp_f32_e32 v41, v41
	v_exp_f32_e32 v42, v42
	v_exp_f32_e32 v43, v43
	v_exp_f32_e32 v44, v44
	v_exp_f32_e32 v45, v45
	v_exp_f32_e32 v46, v46
	v_exp_f32_e32 v47, v47
	v_cndmask_b32_e64 v32, 0, v32, s[54:55]
	v_cndmask_b32_e64 v33, 0, v33, s[60:61]
	v_cndmask_b32_e64 v34, 0, v34, s[64:65]
	v_cndmask_b32_e64 v35, 0, v35, s[62:63]
	v_cndmask_b32_e64 v36, 0, v36, s[94:95]
	v_cndmask_b32_e64 v37, 0, v37, s[52:53]
	v_cndmask_b32_e64 v38, 0, v38, s[2:3]
	v_cndmask_b32_e64 v39, 0, v39, s[58:59]
	v_cndmask_b32_e64 v40, 0, v40, s[14:15]
	v_cndmask_b32_e64 v41, 0, v41, s[16:17]
	v_cndmask_b32_e64 v42, 0, v42, s[18:19]
	v_cndmask_b32_e64 v43, 0, v43, s[20:21]
	v_cndmask_b32_e64 v44, 0, v44, s[22:23]
	v_cndmask_b32_e64 v45, 0, v45, s[24:25]
	v_cndmask_b32_e64 v46, 0, v46, s[26:27]
	v_cndmask_b32_e64 v47, 0, v47, s[28:29]
	v_cvt_pk_bf16_f32 v242, v32, v33
	v_cvt_pk_bf16_f32 v243, v34, v35
	v_cvt_pk_bf16_f32 v244, v36, v37
	v_cvt_pk_bf16_f32 v245, v38, v39
	v_cvt_pk_bf16_f32 v246, v40, v41
	v_cvt_pk_bf16_f32 v247, v42, v43
	v_cvt_pk_bf16_f32 v248, v44, v45
	v_cvt_pk_bf16_f32 v249, v46, v47
	v_add_f32_e32 v97, v32, v33
	v_add_f32_e32 v169, v34, v35
	v_add_f32_e32 v97, v97, v36
	v_add_f32_e32 v169, v169, v37
	v_add_f32_e32 v97, v97, v38
	v_add_f32_e32 v169, v169, v39
	v_add_f32_e32 v97, v97, v40
	v_add_f32_e32 v169, v169, v41
	v_add_f32_e32 v97, v97, v42
	v_add_f32_e32 v169, v169, v43
	v_add_f32_e32 v97, v97, v44
	v_add_f32_e32 v169, v169, v45
	v_add_f32_e32 v97, v97, v46
	v_add_f32_e32 v169, v169, v47
	v_mfma_f32_32x32x16_bf16 v[16:31], v[170:173], v[242:245], v[16:31]
	v_mfma_f32_32x32x16_bf16 v[0:15], v[178:181], v[242:245], v[0:15]
	v_add_f32_e32 v97, v97, v169
	v_mfma_f32_32x32x16_bf16 v[16:31], v[174:177], v[246:249], v[16:31]
	v_mfma_f32_32x32x16_bf16 v[0:15], v[182:185], v[246:249], v[0:15]
	v_add_f32_e32 v166, v166, v97
	s_mov_b64 s[34:35], 0x80
	s_mov_b64 s[44:45], 0x80
	s_branch .LBB0_520
